# v43 + scan-loop lane reductions: v_mov_b32_dpp + v_add_f32 fused into one v_add_f32_dpp (6 sites)
# baseline (speedup 1.0000x reference)
; template <bool PA> ...
;     ...
;             float rv[8], kk[8], av[8], kd[8], lw[8]; u32x4_t tld = (u32x4_t){0u, 0u, 0u, 0u}, vraw = (u32x4_t){0u, 0u, 0u, 0u};
;             {
;                 const size_t row = cbase + (d ? 63 - j : j);
;                 asm volatile("" ::: "memory");
;                 if (haveT && tlow) tld = *(const u32x4_t*)(tbuf + ((size_t)strm * NCHA + p) * 2304 + tunit * 8);
;                 *(u32x4_t*)(MAT(4) + j * 72 + c8) = *(const u32x4_t*)(HWb + row * 128 + d * 64 + c8);
;                 *(u32x4_t*)(MAT(5) + j * 72 + c8) = *(const u32x4_t*)(HAb + row * 128 + d * 64 + c8);
;                 const u32x4_t rw = *(const u32x4_t*)(Rb + row * 1024 + hc8), kw = *(const u32x4_t*)(Kb + row * 1024 + hc8), vw = *(const u32x4_t*)(Vb + row * 1024 + hc8);
;                 __syncthreads();
;                 { f32x4_t za[2], xa[2]; za[0] = (f32x4_t){0.f, 0.f, 0.f, 0.f}; za[1] = za[0]; xa[0] = za[0]; xa[1] = za[0];
;                   mm2(za, MAT(4), w2T, mt, ntb, r16, kq); mm2(xa, MAT(5), a2T, mt, ntb, r16, kq);
; #pragma unroll
;                   for (int i = 0; i < 2; ++i)
; #pragma unroll
;                       for (int e = 0; e < 4; ++e) { zbuf[(16 * mt + 4 * kq + e) * 64 + 16 * (ntb + i) + r16] = za[i][e]; abuf[(16 * mt + 4 * kq + e) * 64 + 16 * (ntb + i) + r16] = xa[i][e]; } }
;                 __syncthreads();
.LBB0_153:
	s_nop 0
	s_waitcnt vmcnt(2)
	ds_write_b128 v91, v[232:235] offset:36864
	ds_write_b128 v91, v[236:239] offset:46080
	v_mov_b32_e32 v10, v228
	v_mov_b32_e32 v11, v229
	v_mov_b32_e32 v12, v230
	v_mov_b32_e32 v13, v231
	v_mov_b32_e32 v18, v240
	v_mov_b32_e32 v19, v241
	v_mov_b32_e32 v20, v242
	v_mov_b32_e32 v21, v243
	v_mov_b32_e32 v22, v244
	v_mov_b32_e32 v23, v245
	v_mov_b32_e32 v24, v246
	v_mov_b32_e32 v25, v247
	v_mov_b32_e32 v14, v248
	v_mov_b32_e32 v15, v249
	v_mov_b32_e32 v16, v250
	v_mov_b32_e32 v17, v251
	s_and_b64 s[0:1], vcc, exec
	s_cselect_b32 s0, s12, s18
	s_cselect_b32 s1, 64, 0xffffffc0
	v_lshl_add_u32 v80, s0, 6, v130
	v_ashrrev_i32_e32 v81, 31, v80
	s_add_i32 s0, s12, 1
	s_cmp_lt_i32 s0, s13
	s_cselect_b32 s1, s1, 0
	v_add_u32_e32 v226, s1, v80
	s_and_saveexec_b64 s[0:1], s[36:37]
	global_load_dwordx4 v[228:231], v[78:79], off
	s_or_b64 exec, exec, s[0:1]
	v_ashrrev_i32_e32 v227, 31, v226
	v_lshlrev_b64 v[224:225], 8, v[226:227]
	v_lshl_add_u64 v[222:223], v[66:67], 0, v[224:225]
	global_load_dwordx4 v[232:235], v[222:223], off
	v_lshl_add_u64 v[222:223], v[68:69], 0, v[224:225]
	global_load_dwordx4 v[236:239], v[222:223], off
	v_lshlrev_b64 v[224:225], 11, v[226:227]
	v_lshl_add_u64 v[222:223], v[70:71], 0, v[224:225]
	global_load_dwordx4 v[240:243], v[222:223], off
	v_lshl_add_u64 v[222:223], v[72:73], 0, v[224:225]
	global_load_dwordx4 v[244:247], v[222:223], off
	v_lshl_add_u64 v[222:223], v[74:75], 0, v[224:225]
	global_load_dwordx4 v[248:251], v[222:223], off
	s_waitcnt lgkmcnt(0)
	s_barrier
	ds_read_b128 v[178:181], v92 offset:36864
	ds_read_b128 v[182:185], v93
	ds_read_b128 v[186:189], v93 offset:2304
	ds_read_b128 v[190:193], v92 offset:36928
	ds_read_b128 v[204:207], v93 offset:64
	ds_read_b128 v[208:211], v93 offset:2368
	ds_read_b128 v[212:215], v92 offset:46080
	ds_read_b128 v[216:219], v94
	ds_read_b128 v[220:223], v94 offset:2304
	ds_read_b128 v[224:227], v92 offset:46144
	s_nop 0
	s_nop 0
	s_nop 0
	s_waitcnt lgkmcnt(8)
	v_mfma_f32_16x16x32_bf16 v[30:33], v[178:181], v[182:185], 0
	ds_read_b128 v[182:185], v94 offset:64
	s_nop 0
	v_lshlrev_b32_e32 v0, 16, v18
	s_waitcnt lgkmcnt(8)
	v_mfma_f32_16x16x32_bf16 v[26:29], v[178:181], v[186:189], 0
	ds_read_b128 v[178:181], v94 offset:2368
	s_nop 0
	s_nop 0
	v_and_b32_e32 v131, 0xffff0000, v18
	s_nop 0
	v_and_b32_e32 v162, 0xffff0000, v24
	s_waitcnt lgkmcnt(7)
	v_mfma_f32_16x16x32_bf16 v[30:33], v[190:193], v[204:207], v[30:33]
	s_nop 0
	v_lshlrev_b32_e32 v141, 16, v21
	v_and_b32_e32 v143, 0xffff0000, v21
	s_waitcnt lgkmcnt(6)
	v_mfma_f32_16x16x32_bf16 v[26:29], v[190:193], v[208:211], v[26:29]
	s_nop 0
	s_nop 0
	s_nop 0
	v_lshlrev_b32_e32 v158, 16, v25
	s_waitcnt lgkmcnt(4)
	v_mfma_f32_16x16x32_bf16 v[38:41], v[212:215], v[216:219], 0
	v_and_b32_e32 v154, 0xffff0000, v25
	s_waitcnt lgkmcnt(3)
	v_mfma_f32_16x16x32_bf16 v[34:37], v[212:215], v[220:223], 0
	s_nop 0
	s_nop 0
	s_waitcnt lgkmcnt(1)
	v_mfma_f32_16x16x32_bf16 v[38:41], v[224:227], v[182:185], v[38:41]
	s_nop 0
	s_waitcnt lgkmcnt(0)
	v_mfma_f32_16x16x32_bf16 v[34:37], v[224:227], v[178:181], v[34:37]
	s_nop 4
	ds_write2st64_b32 v119, v30, v38 offset1:64
	ds_write2st64_b32 v120, v31, v39 offset1:64
	ds_write2st64_b32 v121, v32, v40 offset1:64
	ds_write2st64_b32 v122, v33, v41 offset1:64
	ds_write2st64_b32 v123, v26, v34 offset1:64
	ds_write2st64_b32 v124, v27, v35 offset1:64
	ds_write2st64_b32 v125, v28, v36 offset1:64
	ds_write2st64_b32 v126, v29, v37 offset1:64
	s_waitcnt lgkmcnt(0)
	s_barrier
; __device__ __forceinline__ float sigmoidf_(float x) { return __builtin_amdgcn_rcpf(1.0f + __expf(-x)); }
; template <bool PA> ...
;     ...
;                 float ss = 0.f, bsum = 0.f;
; #pragma unroll
;                 for (int e = 0; e < 8; ++e) { kk[e] = kv[e] * cst[128 + c8 + e]; ss += kk[e] * kk[e]; }
;                 ss += __shfl_xor(ss, 1); ss += __shfl_xor(ss, 2); ss += __shfl_xor(ss, 4);
;                 const float inv = rsqrtf(fmaxf(ss, 1e-24f));
; #pragma unroll
;                 for (int e = 0; e < 8; ++e) { av[e] = sigmoidf_(aa[e]); lw[e] = -0.6065306597f * sigmoidf_(z[e]); kd[e] = kv[e] * (1.0f + (av[e] - 1.0f) * cst[192 + c8 + e]); kk[e] *= inv; bsum += rv[e] * kd[e] * cst[256 + c8 + e]; }
;                 bsum += __shfl_xor(bsum, 1); bsum += __shfl_xor(bsum, 2); bsum += __shfl_xor(bsum, 4);
;                 if (!PA && part == 0) beta[((size_t)d * SLAB + row) * 16 + head] = bsum;
	v_lshlrev_b32_e32 v39, 16, v22
	v_and_b32_e32 v36, 0xffff0000, v22
	v_lshlrev_b32_e32 v133, 16, v19
	v_and_b32_e32 v135, 0xffff0000, v19
	v_lshlrev_b32_e32 v35, 16, v23
	v_and_b32_e32 v34, 0xffff0000, v23
	v_lshlrev_b32_e32 v137, 16, v20
	v_and_b32_e32 v139, 0xffff0000, v20
	v_lshlrev_b32_e32 v38, 16, v24
	ds_read_b128 v[18:21], v95
	ds_read_b128 v[22:25], v95 offset:16
	ds_read_b128 v[144:147], v95 offset:16384
	ds_read_b128 v[148:151], v95 offset:16400
	ds_read_b128 v[26:29], v96
	ds_read_b128 v[30:33], v96 offset:16
	ds_read_b128 v[164:167], v96 offset:256
	ds_read_b128 v[168:171], v96 offset:272
	s_waitcnt lgkmcnt(1)
	v_add_f32_e32 v153, v144, v164
	s_waitcnt lgkmcnt(0)
	v_add_f32_e32 v37, v148, v168
	v_add_f32_e32 v152, v145, v165
	v_add_f32_e32 v164, v149, v169
	v_add_f32_e32 v41, v146, v166
	v_add_f32_e32 v161, v150, v170
	v_add_f32_e32 v40, v147, v167
	v_add_f32_e32 v157, v151, v171
	ds_read_b128 v[144:147], v96 offset:512
	ds_read_b128 v[148:151], v96 offset:528
	ds_read_b128 v[168:171], v96 offset:768
	ds_read_b128 v[172:175], v96 offset:1024
	s_waitcnt lgkmcnt(3)
	v_mul_f32_e32 v134, v145, v36
	v_mul_f32_e32 v132, v144, v39
	v_mul_f32_e32 v155, v134, v134
	v_fmac_f32_e32 v155, v132, v132
	v_mul_f32_e32 v136, v146, v35
	v_fmac_f32_e32 v155, v136, v136
	v_mul_f32_e32 v138, v147, v34
	v_fmac_f32_e32 v155, v138, v138
	s_waitcnt lgkmcnt(2)
	v_mul_f32_e32 v140, v148, v38
	v_and_b32_e32 v147, 64, v198
	v_fmac_f32_e32 v155, v140, v140
	v_mul_f32_e32 v142, v149, v162
	v_xor_b32_e32 v146, 1, v198
	v_add_u32_e32 v147, 64, v147
	v_fmac_f32_e32 v155, v142, v142
	v_mul_f32_e32 v144, v150, v158
	v_cmp_lt_i32_e64 s[92:93], v146, v147
	v_fmac_f32_e32 v155, v144, v144
	v_mul_f32_e32 v145, v151, v154
	v_cndmask_b32_e64 v146, v198, v146, s[92:93]
	v_fmac_f32_e32 v155, v145, v145
	v_lshlrev_b32_e32 v146, 2, v146
	s_nop 1
	v_add_f32_dpp v148, v155, v155 quad_perm:[1,0,3,2] row_mask:0xf bank_mask:0xf
	v_xor_b32_e32 v149, 2, v198
	v_cmp_lt_i32_e64 s[92:93], v149, v147
	s_waitcnt lgkmcnt(0)
	v_cndmask_b32_e64 v149, v198, v149, s[92:93]
	v_lshlrev_b32_e32 v166, 2, v149
	s_nop 1
	v_add_f32_dpp v149, v148, v148 quad_perm:[2,3,0,1] row_mask:0xf bank_mask:0xf
	s_waitcnt lgkmcnt(0)
	v_xor_b32_e32 v148, 4, v198
	v_cmp_lt_i32_e64 s[92:93], v148, v147
	s_nop 1
	v_cndmask_b32_e64 v147, v198, v148, s[92:93]
	v_mul_f32_e32 v148, 0xbfb8aa3b, v153
	v_exp_f32_e32 v148, v148
	v_lshlrev_b32_e32 v147, 2, v147
	s_nop 1
	v_mov_b32_dpp v150, v149 row_half_mirror row_mask:0xf bank_mask:0xf
	v_add_f32_e32 v148, 1.0, v148
	v_rcp_f32_e32 v148, v148
	s_nop 0
	v_add_f32_e32 v151, -1.0, v148
	v_fma_f32 v151, v151, v168, 1.0
	v_mul_f32_e32 v151, v151, v39
	v_mul_f32_e32 v39, v151, v0
	v_fma_f32 v167, v172, v39, 0
	v_mul_f32_e32 v39, 0xbfb8aa3b, v152
	v_exp_f32_e32 v39, v39
	s_nop 0
	v_add_f32_e32 v39, 1.0, v39
	v_rcp_f32_e32 v152, v39
	s_nop 0
	v_add_f32_e32 v39, -1.0, v152
	v_fma_f32 v39, v39, v169, 1.0
	v_mul_f32_e32 v153, v39, v36
	v_mul_f32_e32 v36, v153, v131
	v_fmac_f32_e32 v167, v173, v36
	v_mul_f32_e32 v36, 0xbfb8aa3b, v41
	v_exp_f32_e32 v36, v36
	s_nop 0
	v_add_f32_e32 v36, 1.0, v36
	v_rcp_f32_e32 v155, v36
	s_nop 0
	v_add_f32_e32 v36, -1.0, v155
	v_fma_f32 v36, v36, v170, 1.0
	v_mul_f32_e32 v156, v36, v35
	v_mul_f32_e32 v35, v156, v133
	v_fmac_f32_e32 v167, v174, v35
	v_mul_f32_e32 v35, 0xbfb8aa3b, v40
	v_exp_f32_e32 v35, v35
	s_nop 0
	v_add_f32_e32 v35, 1.0, v35
	v_rcp_f32_e32 v159, v35
	s_nop 0
	v_add_f32_e32 v35, -1.0, v159
	v_fma_f32 v35, v35, v171, 1.0
	v_mul_f32_e32 v160, v35, v34
	v_mul_f32_e32 v34, v160, v135
	v_fmac_f32_e32 v167, v175, v34
	v_mul_f32_e32 v34, 0xbfb8aa3b, v37
	v_exp_f32_e32 v34, v34
	s_nop 0
	v_add_f32_e32 v34, 1.0, v34
	v_rcp_f32_e32 v163, v34
	ds_read_b128 v[34:37], v96 offset:784
	v_add_f32_e32 v39, -1.0, v163
	s_waitcnt lgkmcnt(0)
	v_fma_f32 v34, v39, v34, 1.0
	v_mul_f32_e32 v165, v34, v38
	ds_read_b128 v[38:41], v96 offset:1040
	v_mul_f32_e32 v34, v165, v137
	s_waitcnt lgkmcnt(0)
	v_fmac_f32_e32 v167, v38, v34
	v_mul_f32_e32 v34, 0xbfb8aa3b, v164
	v_exp_f32_e32 v34, v34
	s_nop 0
	v_add_f32_e32 v34, 1.0, v34
	v_rcp_f32_e32 v38, v34
	s_nop 0
	v_add_f32_e32 v34, -1.0, v38
	v_fma_f32 v34, v34, v35, 1.0
	v_mul_f32_e32 v162, v34, v162
	v_mul_f32_e32 v34, v162, v139
	v_fmac_f32_e32 v167, v39, v34
	v_mul_f32_e32 v34, 0xbfb8aa3b, v161
	v_exp_f32_e32 v34, v34
	s_nop 0
	v_add_f32_e32 v34, 1.0, v34
	v_rcp_f32_e32 v39, v34
	s_nop 0
	v_add_f32_e32 v34, -1.0, v39
	v_fma_f32 v34, v34, v36, 1.0
	v_mul_f32_e32 v36, v34, v158
	v_mul_f32_e32 v34, v36, v141
	v_fmac_f32_e32 v167, v40, v34
	v_mul_f32_e32 v34, 0xbfb8aa3b, v157
	v_exp_f32_e32 v34, v34
	s_nop 0
	v_add_f32_e32 v34, 1.0, v34
	v_rcp_f32_e32 v40, v34
	s_nop 0
	v_add_f32_e32 v34, -1.0, v40
	v_fma_f32 v34, v34, v37, 1.0
	v_mul_f32_e32 v37, v34, v154
	v_mul_f32_e32 v34, v37, v143
	v_fmac_f32_e32 v167, v41, v34
	s_nop 1
	v_add_f32_dpp v34, v167, v167 quad_perm:[1,0,3,2] row_mask:0xf bank_mask:0xf
	s_waitcnt lgkmcnt(0)
	s_nop 1
	v_add_f32_dpp v34, v34, v34 quad_perm:[2,3,0,1] row_mask:0xf bank_mask:0xf
	s_waitcnt lgkmcnt(0)
	s_nop 1
	v_mov_b32_dpp v35, v34 row_half_mirror row_mask:0xf bank_mask:0xf
	s_and_saveexec_b64 s[0:1], s[44:45]
	s_cbranch_execz .LBB0_157
	v_lshl_add_u64 v[146:147], s[24:25], 0, v[80:81]
	v_lshlrev_b64 v[146:147], 6, v[146:147]
	v_lshl_add_u64 v[146:147], s[20:21], 0, v[146:147]
	s_waitcnt lgkmcnt(0)
	v_add_f32_e32 v34, v34, v35
	global_store_dword v[146:147], v34, off

; template <bool PA> ...
;     ...
;             float rv[8], kk[8], av[8], kd[8], lw[8]; u32x4_t tld = (u32x4_t){0u, 0u, 0u, 0u}, vraw = (u32x4_t){0u, 0u, 0u, 0u};
;             {
;                 const size_t row = cbase + (d ? 63 - j : j);
;                 asm volatile("" ::: "memory");
;                 if (haveT && tlow) tld = *(const u32x4_t*)(tbuf + ((size_t)strm * NCHA + p) * 2304 + tunit * 8);
;                 *(u32x4_t*)(MAT(4) + j * 72 + c8) = *(const u32x4_t*)(HWb + row * 128 + d * 64 + c8);
;                 *(u32x4_t*)(MAT(5) + j * 72 + c8) = *(const u32x4_t*)(HAb + row * 128 + d * 64 + c8);
;                 const u32x4_t rw = *(const u32x4_t*)(Rb + row * 1024 + hc8), kw = *(const u32x4_t*)(Kb + row * 1024 + hc8), vw = *(const u32x4_t*)(Vb + row * 1024 + hc8);
;                 __syncthreads();
;                 { f32x4_t za[2], xa[2]; za[0] = (f32x4_t){0.f, 0.f, 0.f, 0.f}; za[1] = za[0]; xa[0] = za[0]; xa[1] = za[0];
;                   mm2(za, MAT(4), w2T, mt, ntb, r16, kq); mm2(xa, MAT(5), a2T, mt, ntb, r16, kq);
; #pragma unroll
;                   for (int i = 0; i < 2; ++i)
; #pragma unroll
;                       for (int e = 0; e < 4; ++e) { zbuf[(16 * mt + 4 * kq + e) * 64 + 16 * (ntb + i) + r16] = za[i][e]; abuf[(16 * mt + 4 * kq + e) * 64 + 16 * (ntb + i) + r16] = xa[i][e]; } }
;                 __syncthreads();
.LBB0_213:
	s_waitcnt vmcnt(1)
	ds_write_b128 v68, v[232:235] offset:36864
	ds_write_b128 v68, v[236:239] offset:46080
	v_mov_b32_e32 v22, v240
	v_mov_b32_e32 v23, v241
	v_mov_b32_e32 v24, v242
	v_mov_b32_e32 v25, v243
	v_mov_b32_e32 v26, v244
	v_mov_b32_e32 v27, v245
	v_mov_b32_e32 v28, v246
	v_mov_b32_e32 v29, v247
	v_mov_b32_e32 v18, v248
	v_mov_b32_e32 v19, v249
	v_mov_b32_e32 v20, v250
	v_mov_b32_e32 v21, v251
	s_and_b64 s[12:13], s[74:75], exec
	s_cselect_b32 s12, s20, s24
	s_cselect_b32 s13, 64, 0xffffffc0
	v_lshl_add_u32 v226, s12, 6, v160
	s_add_i32 s12, s20, 1
	s_cmp_lt_i32 s12, s21
	s_cselect_b32 s13, s13, 0
	v_add_u32_e32 v226, s13, v226
	v_ashrrev_i32_e32 v227, 31, v226
	v_lshlrev_b64 v[224:225], 8, v[226:227]
	v_lshl_add_u64 v[222:223], v[90:91], 0, v[224:225]
	global_load_dwordx4 v[232:235], v[222:223], off
	v_lshl_add_u64 v[222:223], v[92:93], 0, v[224:225]
	global_load_dwordx4 v[236:239], v[222:223], off
	v_lshlrev_b64 v[224:225], 11, v[226:227]
	v_lshl_add_u64 v[222:223], v[94:95], 0, v[224:225]
	global_load_dwordx4 v[240:243], v[222:223], off
	v_lshl_add_u64 v[222:223], v[96:97], 0, v[224:225]
	global_load_dwordx4 v[244:247], v[222:223], off
	v_lshl_add_u64 v[222:223], v[98:99], 0, v[224:225]
	global_load_dwordx4 v[248:251], v[222:223], off
	s_waitcnt lgkmcnt(0)
	s_barrier
	ds_read_b128 v[186:189], v69 offset:36864
	ds_read_b128 v[190:193], v108
	ds_read_b128 v[204:207], v108 offset:2304
	ds_read_b128 v[208:211], v69 offset:36928
	ds_read_b128 v[212:215], v108 offset:64
	ds_read_b128 v[216:219], v108 offset:2368
	ds_read_b128 v[220:223], v69 offset:46080
	ds_read_b128 v[224:227], v109
	s_nop 0
	s_nop 0
	s_nop 0
	s_waitcnt lgkmcnt(6)
	v_mfma_f32_16x16x32_bf16 v[34:37], v[186:189], v[190:193], 0
	ds_read_b128 v[190:193], v109 offset:2304
	s_nop 0
	v_lshlrev_b32_e32 v161, 16, v26
	s_waitcnt lgkmcnt(6)
	v_mfma_f32_16x16x32_bf16 v[30:33], v[186:189], v[204:207], 0
	ds_read_b128 v[186:189], v69 offset:46144
	ds_read_b128 v[204:207], v109 offset:64
	s_nop 0
	s_nop 0
	v_and_b32_e32 v163, 0xffff0000, v26
	v_lshlrev_b32_e32 v165, 16, v27
	s_waitcnt lgkmcnt(6)
	v_mfma_f32_16x16x32_bf16 v[34:37], v[208:211], v[212:215], v[34:37]
	ds_read_b128 v[212:215], v109 offset:2368
	s_nop 0
	v_and_b32_e32 v167, 0xffff0000, v27
	v_lshlrev_b32_e32 v169, 16, v28
	s_waitcnt lgkmcnt(6)
	v_mfma_f32_16x16x32_bf16 v[30:33], v[208:211], v[216:219], v[30:33]
	s_nop 0
	s_nop 0
	s_nop 0
	v_and_b32_e32 v171, 0xffff0000, v28
	s_waitcnt lgkmcnt(4)
	v_mfma_f32_16x16x32_bf16 v[42:45], v[220:223], v[224:227], 0
	v_lshlrev_b32_e32 v173, 16, v29
	v_and_b32_e32 v175, 0xffff0000, v29
	s_waitcnt lgkmcnt(3)
	v_mfma_f32_16x16x32_bf16 v[38:41], v[220:223], v[190:193], 0
	s_nop 0
	s_nop 0
	s_waitcnt lgkmcnt(1)
	v_mfma_f32_16x16x32_bf16 v[42:45], v[186:189], v[204:207], v[42:45]
	s_nop 0
	s_waitcnt lgkmcnt(0)
	v_mfma_f32_16x16x32_bf16 v[38:41], v[186:189], v[212:215], v[38:41]
	s_nop 4
	ds_write2st64_b32 v144, v34, v42 offset1:64
	ds_write2st64_b32 v145, v35, v43 offset1:64
	ds_write2st64_b32 v148, v36, v44 offset1:64
	ds_write2st64_b32 v149, v37, v45 offset1:64
	ds_write2st64_b32 v150, v30, v38 offset1:64
	ds_write2st64_b32 v151, v31, v39 offset1:64
	ds_write2st64_b32 v152, v32, v40 offset1:64
	ds_write2st64_b32 v153, v33, v41 offset1:64
	s_waitcnt lgkmcnt(0)
	s_barrier
; __device__ __forceinline__ float sigmoidf_(float x) { return __builtin_amdgcn_rcpf(1.0f + __expf(-x)); }
; template <bool PA> ...
;     ...
;                 float ss = 0.f, bsum = 0.f;
; #pragma unroll
;                 for (int e = 0; e < 8; ++e) { kk[e] = kv[e] * cst[128 + c8 + e]; ss += kk[e] * kk[e]; }
;                 ss += __shfl_xor(ss, 1); ss += __shfl_xor(ss, 2); ss += __shfl_xor(ss, 4);
;                 const float inv = rsqrtf(fmaxf(ss, 1e-24f));
; #pragma unroll
;                 for (int e = 0; e < 8; ++e) { av[e] = sigmoidf_(aa[e]); lw[e] = -0.6065306597f * sigmoidf_(z[e]); kd[e] = kv[e] * (1.0f + (av[e] - 1.0f) * cst[192 + c8 + e]); kk[e] *= inv; bsum += rv[e] * kd[e] * cst[256 + c8 + e]; }
;                 bsum += __shfl_xor(bsum, 1); bsum += __shfl_xor(bsum, 2); bsum += __shfl_xor(bsum, 4);
;                 if (!PA && part == 0) beta[((size_t)d * SLAB + row) * 16 + head] = bsum;
;                 *(f32x4_t*)(cumb + j * 64 + c8) = (f32x4_t){lw[0], lw[1], lw[2], lw[3]}; *(f32x4_t*)(cumb + j * 64 + c8 + 4) = (f32x4_t){lw[4], lw[5], lw[6], lw[7]};
;             }
;             __syncthreads();
;             { const int c = tid & 63, sg = tid >> 6; float run = 0.f;
; #pragma unroll
;               for (int i = 0; i < 8; ++i) { run += cumb[(8 * sg + i) * 64 + c]; cumb[(8 * sg + i) * 64 + c] = run; }
;               segtot[sg * 64 + c] = run; }
;             __syncthreads();
;             { const int c = tid & 63, sg = tid >> 6; float off = 0.f;
; #pragma unroll
;               for (int s = 0; s < 7; ++s) off += (s < sg) ? segtot[s * 64 + c] : 0.f;
; #pragma unroll
;               for (int i = 0; i < 8; ++i) cumb[(8 * sg + i) * 64 + c] += off; }
	ds_read_b128 v[186:189], v110
	ds_read_b128 v[190:193], v110 offset:16
	ds_read_b128 v[204:207], v111
	ds_read_b128 v[208:211], v111 offset:16
	ds_read_b128 v[212:215], v111 offset:512
	ds_read_b128 v[216:219], v111 offset:528
	s_nop 0
	s_nop 0
	ds_read_b128 v[26:29], v110 offset:16384
	ds_read_b128 v[30:33], v110 offset:16400
	s_nop 0
	s_nop 0
	ds_read_b128 v[34:37], v111 offset:256
	ds_read_b128 v[38:41], v111 offset:272
	s_waitcnt lgkmcnt(2)
	v_add_f32_e32 v42, v186, v204
	s_waitcnt lgkmcnt(2)
	v_add_f32_e32 v50, v190, v208
	v_add_f32_e32 v46, v187, v205
	v_add_f32_e32 v54, v191, v209
	v_add_f32_e32 v49, v188, v206
	v_add_f32_e32 v57, v192, v210
	v_add_f32_e32 v48, v189, v207
	v_add_f32_e32 v56, v193, v211
	s_nop 0
	s_nop 0
	v_and_b32_e32 v45, 64, v198
	v_xor_b32_e32 v44, 1, v198
	v_add_u32_e32 v45, 64, v45
	s_waitcnt lgkmcnt(0)
	v_mul_f32_e32 v164, v213, v163
	v_mul_f32_e32 v162, v212, v161
	v_mul_f32_e32 v43, v164, v164
	v_fmac_f32_e32 v43, v162, v162
	v_mul_f32_e32 v166, v214, v165
	v_fmac_f32_e32 v43, v166, v166
	v_mul_f32_e32 v168, v215, v167
	v_mov_b32_e32 v61, v215
	v_fmac_f32_e32 v43, v168, v168
	s_waitcnt lgkmcnt(0)
	v_mul_f32_e32 v170, v216, v169
	v_fmac_f32_e32 v43, v170, v170
	v_mul_f32_e32 v172, v217, v171
	v_fmac_f32_e32 v43, v172, v172
	v_mul_f32_e32 v174, v218, v173
	v_cmp_lt_i32_e64 s[76:77], v44, v45
	v_fmac_f32_e32 v43, v174, v174
	v_mul_f32_e32 v176, v219, v175
	v_mov_b32_e32 v62, v216
	v_mov_b32_e32 v63, v217
	v_mov_b32_e32 v64, v218
	v_mov_b32_e32 v65, v219
	v_cndmask_b32_e64 v44, v198, v44, s[76:77]
	v_fmac_f32_e32 v43, v176, v176
	v_lshlrev_b32_e32 v44, 2, v44
	s_nop 1
	v_add_f32_dpp v43, v43, v43 quad_perm:[1,0,3,2] row_mask:0xf bank_mask:0xf
	v_mul_f32_e32 v42, 0xbfb8aa3b, v42
	v_mul_f32_e32 v46, 0xbfb8aa3b, v46
	v_exp_f32_e32 v42, v42
	v_exp_f32_e32 v46, v46
	v_mul_f32_e32 v50, 0xbfb8aa3b, v50
	v_mul_f32_e32 v54, 0xbfb8aa3b, v54
	s_waitcnt lgkmcnt(0)
	v_xor_b32_e32 v44, 2, v198
	v_exp_f32_e32 v50, v50
	v_exp_f32_e32 v54, v54
	v_cmp_lt_i32_e64 s[76:77], v44, v45
	v_mul_f32_e32 v49, 0xbfb8aa3b, v49
	v_mul_f32_e32 v48, 0xbfb8aa3b, v48
	v_cndmask_b32_e64 v44, v198, v44, s[76:77]
	v_lshlrev_b32_e32 v44, 2, v44
	v_add_f32_e32 v42, 1.0, v42
	v_add_f32_e32 v46, 1.0, v46
	v_exp_f32_e32 v49, v49
	v_exp_f32_e32 v48, v48
	v_mul_f32_e32 v57, 0xbfb8aa3b, v57
	v_mul_f32_e32 v56, 0xbfb8aa3b, v56
	s_nop 1
	v_add_f32_dpp v146, v43, v43 quad_perm:[2,3,0,1] row_mask:0xf bank_mask:0xf
	v_rcp_f32_e32 v52, v42
	v_rcp_f32_e32 v53, v46
	v_add_f32_e32 v50, 1.0, v50
	v_add_f32_e32 v54, 1.0, v54
	v_exp_f32_e32 v57, v57
	v_exp_f32_e32 v56, v56
	v_rcp_f32_e32 v58, v50
	v_rcp_f32_e32 v59, v54
	v_add_f32_e32 v49, 1.0, v49
	v_add_f32_e32 v48, 1.0, v48
	v_pk_mul_f32 v[46:47], v[52:53], s[30:31] op_sel_hi:[1,0]
	v_rcp_f32_e32 v52, v49
	v_rcp_f32_e32 v53, v48
	v_add_f32_e32 v57, 1.0, v57
	v_add_f32_e32 v56, 1.0, v56
	s_waitcnt lgkmcnt(0)
	v_xor_b32_e32 v43, 4, v198
	v_pk_mul_f32 v[54:55], v[58:59], s[30:31] op_sel_hi:[1,0]
	v_rcp_f32_e32 v58, v57
	v_rcp_f32_e32 v59, v56
	v_cmp_lt_i32_e64 s[76:77], v43, v45
	v_pk_mul_f32 v[48:49], v[52:53], s[30:31] op_sel_hi:[1,0]
	ds_read_b128 v[50:53], v111 offset:784
	v_cndmask_b32_e64 v43, v198, v43, s[76:77]
	v_lshlrev_b32_e32 v43, 2, v43
	s_nop 1
	v_mov_b32_dpp v147, v146 row_half_mirror row_mask:0xf bank_mask:0xf
	ds_read_b128 v[42:45], v111 offset:768
	v_pk_mul_f32 v[56:57], v[58:59], s[30:31] op_sel_hi:[1,0]
	ds_write_b128 v112, v[46:49]
	ds_write_b128 v112, v[54:57] offset:16
	s_waitcnt lgkmcnt(0)
	s_barrier
	ds_read2st64_b32 v[186:187], v159 offset1:1
	ds_read2st64_b32 v[188:189], v159 offset0:2 offset1:3
	ds_read2st64_b32 v[190:191], v159 offset0:4 offset1:5
	ds_read2st64_b32 v[192:193], v159 offset0:6 offset1:7
	s_nop 0
	s_waitcnt lgkmcnt(3)
	v_add_f32_e32 v58, 0, v186
	v_add_f32_e32 v60, v58, v187
	ds_write2st64_b32 v159, v58, v60 offset1:1
	s_nop 0
	s_waitcnt lgkmcnt(0)
	v_add_f32_e32 v58, v60, v188
	v_add_f32_e32 v60, v58, v189
	ds_write2st64_b32 v159, v58, v60 offset0:2 offset1:3
	s_nop 0
	s_waitcnt lgkmcnt(0)
	v_add_f32_e32 v58, v60, v190
	v_add_f32_e32 v60, v58, v191
	ds_write2st64_b32 v159, v58, v60 offset0:4 offset1:5
	s_nop 0
	s_waitcnt lgkmcnt(0)
	v_add_f32_e32 v58, v60, v192
	v_add_f32_e32 v59, v58, v193
	ds_write2st64_b32 v159, v58, v59 offset0:6 offset1:7
	ds_write_b32 v113, v59
	v_mov_b32_e32 v58, 0
	s_waitcnt lgkmcnt(0)
	s_barrier
	s_and_saveexec_b64 s[12:13], s[44:45]
	s_cbranch_execz .LBB0_215
	ds_read_b32 v58, v114
	s_waitcnt lgkmcnt(0)
	v_add_f32_e32 v58, 0, v58
